# seam 0: non-returning arrival and polling of the arrival counter itself (no flag word)
# baseline (speedup 1.0000x reference)
; __device__ __forceinline__ void fast_grid_barrier(unsigned* base, int seam, int tid) {
;     asm volatile("s_waitcnt vmcnt(0)" ::: "memory");
;     __syncthreads();
;     if (tid == 0) {
;         unsigned* cnt = base + seam * 128;
;         unsigned* flg = cnt + 64;
;         __builtin_amdgcn_fence(__ATOMIC_RELEASE, "agent");
;         asm volatile("s_waitcnt vmcnt(0)" ::: "memory");
;         const unsigned old = __hip_atomic_fetch_add(cnt, 1u, __ATOMIC_RELAXED, __HIP_MEMORY_SCOPE_AGENT);
;         if (old == gridDim.x - 1) __hip_atomic_store(flg, 1u, __ATOMIC_RELAXED, __HIP_MEMORY_SCOPE_AGENT);
;         else { unsigned sp = 0; while (__hip_atomic_load(flg, __ATOMIC_RELAXED, __HIP_MEMORY_SCOPE_AGENT) == 0u) { __builtin_amdgcn_s_sleep(2); if (++sp > (1u << 22)) break; } }
;         __builtin_amdgcn_fence(__ATOMIC_ACQUIRE, "agent");
;         asm volatile("s_waitcnt vmcnt(0)" ::: "memory");
;     }
;     __syncthreads();
.LBB0_60:
.LBB0_61:
	s_cmp_lt_i32 s47, 2
	s_cbranch_scc1 .LBB0_78
	s_waitcnt vmcnt(0)
	v_cmp_eq_u32_e32 vcc, 0, v202
	s_barrier
	s_and_saveexec_b64 s[0:1], vcc
	s_cbranch_execz .LBB0_77
	s_load_dword s3, s[84:85], 0xa0
	v_mov_b32_e32 v0, 0
	v_mov_b32_e32 v2, 1
	s_waitcnt vmcnt(0)
	global_atomic_add v0, v2, s[44:45] offset:1024
	s_waitcnt lgkmcnt(0)
	s_mov_b32 s4, 0x8000
.Ls0_loop:
	global_load_dword v1, v0, s[44:45] offset:1024 sc1
	s_waitcnt vmcnt(0)
	v_cmp_le_u32_e32 vcc, s3, v1
	s_cbranch_vccnz .Ls0_done
	s_sleep 1
	s_add_i32 s4, s4, -1
	s_cmp_lg_u32 s4, 0
	s_cbranch_scc1 .Ls0_loop
.Ls0_done:
	s_waitcnt vmcnt(0)
	buffer_inv sc1
	s_waitcnt vmcnt(0)
.LBB0_77:
	s_or_b64 exec, exec, s[0:1]
	s_barrier
